# ssd tile: four masked decay-matrix elements computed branch-free behind one LDS wait
# baseline (speedup 1.0000x reference)
; __device__ __forceinline__ void ssd_tile(const Params& p, int l, int tile, unsigned char* smem) {
;     ...
;     {
;       const int j = tid & 31, ng = tid >> 5;
;       const float tail = __expf(cums[31] - cums[j]);
;       const float dtj = dts[j];
;       const uint4 b0 = *(const uint4*)(Bs + j * 136 + ng * 16), b1 = *(const uint4*)(Bs + j * 136 + ng * 16 + 8);
;       const uint4 x0 = *(const uint4*)(Xs + j * 72 + ng * 8);
;       const unsigned bw[8] = {b0.x, b0.y, b0.z, b0.w, b1.x, b1.y, b1.z, b1.w};
;       const unsigned xw[4] = {x0.x, x0.y, x0.z, x0.w};
; #pragma unroll
;       for (int e = 0; e < 8; ++e) {
;         const unsigned pk = pack2(__uint_as_float(bw[e] << 16) * tail, __uint_as_float(bw[e] & 0xffff0000u) * tail);
;         BtT[(ng * 16 + 2 * e) * 40 + j] = (bf16_t)(pk & 0xffffu);
;         BtT[(ng * 16 + 2 * e + 1) * 40 + j] = (bf16_t)(pk >> 16);
;       }
.LBB0_1516:
	s_and_b32 s67, s28, 1
	s_lshl_b32 s56, s67, 8
	s_add_i32 s70, s56, 0
	s_add_i32 s70, s70, 0x10200
	s_waitcnt vmcnt(8)
	v_mov_b32_e32 v32, s70
	ds_read_b32 v36, v32 offset:252
	v_lshl_add_u32 v32, v104, 2, s70
	ds_read2_b32 v[44:45], v32 offset1:32
	ds_read_b128 v[32:35], v120 offset:17408
	s_mul_i32 s56, s67, 0x2200
	v_add_u32_e32 v60, s56, v84
	v_lshl_add_u32 v130, v94, 2, s70
	s_waitcnt lgkmcnt(1)
	v_sub_f32_e32 v36, v36, v45
	v_mul_f32_e32 v36, 0x3fb8aa3b, v36
	v_exp_f32_e32 v46, v36
	s_waitcnt lgkmcnt(0)
	v_lshlrev_b32_e32 v48, 16, v32
	v_and_b32_e32 v49, 0xffff0000, v32
	ds_read_b128 v[36:39], v120 offset:17424
	ds_read_b128 v[40:43], v125 offset:26112
	v_pk_mul_f32 v[48:49], v[46:47], v[48:49] op_sel_hi:[0,1]
	v_cvt_pk_bf16_f32 v32, v48, v49
	ds_write_b16 v105, v32 offset:30720
	ds_write_b16_d16_hi v106, v32 offset:30800
	v_lshlrev_b32_e32 v32, 16, v33
	v_and_b32_e32 v33, 0xffff0000, v33
	v_pk_mul_f32 v[32:33], v[46:47], v[32:33] op_sel_hi:[0,1]
	v_cvt_pk_bf16_f32 v32, v32, v33
	ds_write_b16 v105, v32 offset:30880
	ds_write_b16_d16_hi v106, v32 offset:30960
	v_lshlrev_b32_e32 v32, 16, v34
	v_and_b32_e32 v33, 0xffff0000, v34
	v_pk_mul_f32 v[32:33], v[46:47], v[32:33] op_sel_hi:[0,1]
	v_cvt_pk_bf16_f32 v32, v32, v33
	ds_write_b16 v105, v32 offset:31040
	ds_write_b16_d16_hi v106, v32 offset:31120
	v_lshlrev_b32_e32 v32, 16, v35
	v_and_b32_e32 v33, 0xffff0000, v35
	v_pk_mul_f32 v[32:33], v[46:47], v[32:33] op_sel_hi:[0,1]
	v_cvt_pk_bf16_f32 v32, v32, v33
	ds_write_b16 v105, v32 offset:31200
	ds_write_b16_d16_hi v106, v32 offset:31280
	s_waitcnt lgkmcnt(9)
	v_lshlrev_b32_e32 v32, 16, v36
	v_and_b32_e32 v33, 0xffff0000, v36
	v_pk_mul_f32 v[32:33], v[46:47], v[32:33] op_sel_hi:[0,1]
	v_cvt_pk_bf16_f32 v32, v32, v33
	ds_write_b16 v105, v32 offset:31360
	ds_write_b16_d16_hi v106, v32 offset:31440
	v_lshlrev_b32_e32 v32, 16, v37
	v_and_b32_e32 v33, 0xffff0000, v37
	v_pk_mul_f32 v[32:33], v[46:47], v[32:33] op_sel_hi:[0,1]
	v_cvt_pk_bf16_f32 v32, v32, v33
	ds_write_b16 v105, v32 offset:31520
	ds_write_b16_d16_hi v106, v32 offset:31600
	v_lshlrev_b32_e32 v32, 16, v38
	v_and_b32_e32 v33, 0xffff0000, v38
	v_pk_mul_f32 v[32:33], v[46:47], v[32:33] op_sel_hi:[0,1]
	v_cvt_pk_bf16_f32 v32, v32, v33
	ds_write_b16 v105, v32 offset:31680
	ds_write_b16_d16_hi v106, v32 offset:31760
	v_lshlrev_b32_e32 v32, 16, v39
	v_and_b32_e32 v33, 0xffff0000, v39
	v_pk_mul_f32 v[32:33], v[46:47], v[32:33] op_sel_hi:[0,1]
	v_cvt_pk_bf16_f32 v32, v32, v33
	ds_write_b16 v105, v32 offset:31840
	ds_write_b16_d16_hi v106, v32 offset:31920
	s_waitcnt lgkmcnt(14)
; __device__ __forceinline__ bf16_t f2bf(float f) { return (bf16_t)(pack2(f, 0.f) & 0xffffu); }
; #define MFMA(a, b, c) __builtin_amdgcn_mfma_f32_16x16x32_bf16(a, b, c, 0, 0, 0)
; __device__ __forceinline__ void ssd_tile(const Params& p, int l, int tile, unsigned char* smem) {
;     ...
;       const uint4 b0 = *(const uint4*)(Bs + j * 136 + ng * 16), b1 = *(const uint4*)(Bs + j * 136 + ng * 16 + 8);
;       const uint4 x0 = *(const uint4*)(Xs + j * 72 + ng * 8);
;       const unsigned bw[8] = {b0.x, b0.y, b0.z, b0.w, b1.x, b1.y, b1.z, b1.w};
;       const unsigned xw[4] = {x0.x, x0.y, x0.z, x0.w};
; #pragma unroll
;       for (int e = 0; e < 8; ++e) {
;         const unsigned pk = pack2(__uint_as_float(bw[e] << 16) * tail, __uint_as_float(bw[e] & 0xffff0000u) * tail);
;         BtT[(ng * 16 + 2 * e) * 40 + j] = (bf16_t)(pk & 0xffffu);
;         BtT[(ng * 16 + 2 * e + 1) * 40 + j] = (bf16_t)(pk >> 16);
;       }
; #pragma unroll
;       for (int e = 0; e < 4; ++e) {
;         const unsigned pk = pack2(__uint_as_float(xw[e] << 16) * dtj, __uint_as_float(xw[e] & 0xffff0000u) * dtj);
;         XdT[(ng * 8 + 2 * e) * 40 + j] = (bf16_t)(pk & 0xffffu);
;         XdT[(ng * 8 + 2 * e + 1) * 40 + j] = (bf16_t)(pk >> 16);
;       }
; #pragma unroll
;       for (int mt = 0; mt < 4; ++mt)
; #pragma unroll
;         for (int t = 0; t < 2; ++t)
; #pragma unroll
;           for (int jj = 0; jj < 4; ++jj) Sb[(mt * 16 + fq * 4 + jj) * 136 + (2 * w + t) * 16 + fr] = f2bf(S[mt][t][jj]);
;       const int mi = w >> 1, nj = w & 1;
;       f32x4 acc = (f32x4){0.f, 0.f, 0.f, 0.f};
; #pragma unroll
;       for (int ks = 0; ks < 4; ++ks) {
;         bf16x8 a = *(const bf16x8*)(Cs + (mi * 16 + fr) * 136 + ks * 32 + fq * 8);
;         bf16x8 bb = *(const bf16x8*)(Bs + (nj * 16 + fr) * 136 + ks * 32 + fq * 8);
;         acc = MFMA(a, bb, acc);
;       }
;       const int jc = nj * 16 + fr;
;       const float cj = cums[jc];
; #pragma unroll
;       for (int jj = 0; jj < 4; ++jj) {
;         const int i = mi * 16 + fq * 4 + jj;
;         const float v = (jc <= i) ? acc[jj] * __expf(cums[i] - cj) : 0.f;
;         Ms[i * 40 + jc] = f2bf(v);
;       }
	v_lshlrev_b32_e32 v32, 16, v40
	v_and_b32_e32 v33, 0xffff0000, v40
	v_pk_mul_f32 v[32:33], v[44:45], v[32:33] op_sel_hi:[0,1]
	v_cvt_pk_bf16_f32 v32, v32, v33
	ds_write_b16 v102, v32 offset:40960
	ds_write_b16_d16_hi v103, v32 offset:41040
	v_lshlrev_b32_e32 v32, 16, v41
	v_and_b32_e32 v33, 0xffff0000, v41
	v_pk_mul_f32 v[32:33], v[44:45], v[32:33] op_sel_hi:[0,1]
	v_cvt_pk_bf16_f32 v32, v32, v33
	ds_write_b16 v102, v32 offset:41120
	ds_write_b16_d16_hi v103, v32 offset:41200
	v_lshlrev_b32_e32 v32, 16, v42
	v_and_b32_e32 v33, 0xffff0000, v42
	v_pk_mul_f32 v[32:33], v[44:45], v[32:33] op_sel_hi:[0,1]
	v_cvt_pk_bf16_f32 v32, v32, v33
	ds_write_b16 v102, v32 offset:41280
	ds_write_b16_d16_hi v103, v32 offset:41360
	v_lshlrev_b32_e32 v32, 16, v43
	v_and_b32_e32 v33, 0xffff0000, v43
	v_pk_mul_f32 v[32:33], v[44:45], v[32:33] op_sel_hi:[0,1]
	v_cvt_pk_bf16_f32 v32, v32, v33
	ds_write_b16 v102, v32 offset:41440
	ds_write_b16_d16_hi v103, v32 offset:41520
	v_cvt_pk_bf16_f32 v32, v28, s0
	ds_write_b16 v101, v32 offset:48640
	v_cvt_pk_bf16_f32 v32, v29, s0
	ds_write_b16 v101, v32 offset:48912
	v_cvt_pk_bf16_f32 v32, v30, s0
	ds_write_b16 v101, v32 offset:49184
	v_cvt_pk_bf16_f32 v32, v31, s0
	ds_write_b16 v101, v32 offset:49456
	v_cvt_pk_bf16_f32 v32, v24, s0
	ds_write_b16 v101, v32 offset:48672
	v_cvt_pk_bf16_f32 v32, v25, s0
	ds_write_b16 v101, v32 offset:48944
	v_cvt_pk_bf16_f32 v32, v26, s0
	ds_write_b16 v101, v32 offset:49216
	v_cvt_pk_bf16_f32 v32, v27, s0
	ds_write_b16 v101, v32 offset:49488
	v_cvt_pk_bf16_f32 v32, v20, s0
	ds_write_b16 v101, v32 offset:52992
	v_cvt_pk_bf16_f32 v32, v21, s0
	ds_write_b16 v101, v32 offset:53264
	v_cvt_pk_bf16_f32 v32, v22, s0
	ds_write_b16 v101, v32 offset:53536
	v_cvt_pk_bf16_f32 v32, v23, s0
	ds_write_b16 v101, v32 offset:53808
	v_cvt_pk_bf16_f32 v32, v16, s0
	ds_write_b16 v101, v32 offset:53024
	v_cvt_pk_bf16_f32 v32, v17, s0
	ds_write_b16 v101, v32 offset:53296
	v_cvt_pk_bf16_f32 v32, v18, s0
	ds_write_b16 v101, v32 offset:53568
	v_cvt_pk_bf16_f32 v32, v19, s0
	ds_write_b16 v101, v32 offset:53840
	v_cvt_pk_bf16_f32 v32, v12, s0
	ds_write_b16 v101, v32 offset:57344
	v_cvt_pk_bf16_f32 v32, v13, s0
	ds_write_b16 v101, v32 offset:57616
	v_cvt_pk_bf16_f32 v32, v14, s0
	ds_write_b16 v101, v32 offset:57888
	v_cvt_pk_bf16_f32 v32, v15, s0
	ds_write_b16 v101, v32 offset:58160
	v_cvt_pk_bf16_f32 v32, v8, s0
	ds_write_b16 v101, v32 offset:57376
	v_cvt_pk_bf16_f32 v32, v9, s0
	ds_write_b16 v101, v32 offset:57648
	v_cvt_pk_bf16_f32 v32, v10, s0
	ds_write_b16 v101, v32 offset:57920
	v_cvt_pk_bf16_f32 v32, v11, s0
	ds_write_b16 v101, v32 offset:58192
	v_cvt_pk_bf16_f32 v32, v4, s0
	ds_write_b16 v101, v32 offset:61696
	v_cvt_pk_bf16_f32 v32, v5, s0
	ds_write_b16 v101, v32 offset:61968
	v_cvt_pk_bf16_f32 v32, v6, s0
	ds_write_b16 v101, v32 offset:62240
	v_cvt_pk_bf16_f32 v32, v7, s0
	ds_write_b16 v101, v32 offset:62512
	v_cvt_pk_bf16_f32 v32, v0, s0
	ds_write_b16 v101, v32 offset:61728
	v_cvt_pk_bf16_f32 v32, v1, s0
	ds_write_b16 v101, v32 offset:62000
	v_cvt_pk_bf16_f32 v32, v2, s0
	ds_write_b16 v101, v32 offset:62272
	v_cvt_pk_bf16_f32 v32, v3, s0
	ds_write_b16 v101, v32 offset:62544
	ds_read_b128 v[32:35], v60
	ds_read_b128 v[36:39], v60 offset:64
	ds_read_b128 v[40:43], v95 offset:17408
	ds_read_b128 v[44:47], v95 offset:17472
	s_waitcnt lgkmcnt(1)
	v_mfma_f32_16x16x32_bf16 v[32:35], v[32:35], v[40:43], 0
	ds_read_b128 v[40:43], v60 offset:128
	s_waitcnt lgkmcnt(1)
	v_mfma_f32_16x16x32_bf16 v[32:35], v[36:39], v[44:47], v[32:35]
	ds_read_b128 v[44:47], v60 offset:192
	ds_read_b128 v[36:39], v95 offset:17536
	ds_read_b128 v[48:51], v95 offset:17600
	s_waitcnt lgkmcnt(1)
	v_mfma_f32_16x16x32_bf16 v[32:35], v[40:43], v[36:39], v[32:35]
	v_lshl_add_u32 v36, v93, 2, s70
	ds_read_b32 v36, v36 offset:128
	v_mov_b32_e32 v37, 0
	s_waitcnt lgkmcnt(1)
	v_mfma_f32_16x16x32_bf16 v[32:35], v[44:47], v[48:51], v[32:35]
	ds_read2_b32 v[40:41], v130 offset0:32 offset1:33
	ds_read2_b32 v[42:43], v130 offset0:34 offset1:35
	s_waitcnt lgkmcnt(0)
	v_sub_f32_e32 v40, v40, v36
	v_sub_f32_e32 v41, v41, v36
	v_sub_f32_e32 v42, v42, v36
	v_sub_f32_e32 v43, v43, v36
	v_mul_f32_e32 v40, 0x3fb8aa3b, v40
	v_mul_f32_e32 v41, 0x3fb8aa3b, v41
	v_mul_f32_e32 v42, 0x3fb8aa3b, v42
	v_mul_f32_e32 v43, 0x3fb8aa3b, v43
	v_exp_f32_e32 v40, v40
	v_exp_f32_e32 v41, v41
	v_exp_f32_e32 v42, v42
	v_exp_f32_e32 v43, v43
	s_nop 0
	v_mul_f32_e32 v40, v32, v40
	v_mul_f32_e32 v41, v33, v41
	v_mul_f32_e32 v42, v34, v42
	v_mul_f32_e32 v43, v35, v43
	v_cvt_pk_bf16_f32 v40, v40, s0
	v_cvt_pk_bf16_f32 v41, v41, s0
	v_cvt_pk_bf16_f32 v42, v42, s0
	v_cvt_pk_bf16_f32 v43, v43, s0
	v_cndmask_b32_e64 v37, 0, v40, s[54:55]
	v_cndmask_b32_e64 v44, 0, v41, s[52:53]
	v_cndmask_b32_e64 v45, 0, v42, s[50:51]
	v_cndmask_b32_e64 v33, 0, v43, s[48:49]
	ds_write_b16 v99, v37 offset:46080
	ds_write_b16 v99, v44 offset:46160
	ds_write_b16 v99, v45 offset:46240
	v_mov_b32_e32 v32, 0
	v_readlane_b32 s0, v253, 34
	s_add_i32 s64, s69, 0xffffeee0
	v_readlane_b32 s1, v253, 35
	s_and_b64 s[56:57], s[0:1], exec
	s_cselect_b32 s64, s66, s64
	s_sub_i32 s68, s69, 32
	s_and_b64 s[56:57], s[0:1], exec
	s_cselect_b32 s56, s66, s68
	s_cmp_lt_u32 s28, 7
	ds_write_b16 v99, v33 offset:46320
	s_cselect_b32 s71, s64, s56
	v_mov_b32_e32 v33, 0
	v_mov_b32_e32 v34, 0
	v_mov_b32_e32 v35, 0
	s_waitcnt lgkmcnt(0)
	s_barrier
	s_and_saveexec_b64 s[56:57], s[42:43]
	s_cbranch_execz .LBB0_1526
	v_add_u32_e32 v32, s71, v87
	v_mad_i64_i32 v[32:33], s[72:73], v32, s39, v[76:77]
	global_load_dwordx4 v[32:35], v[32:33], off
